# first norm phase reads x with plain loads (not non-temporal) so that the first residual epilogue finds it in the memory-side cache
# baseline (speedup 1.0000x reference)
; __device__ __forceinline__ void norm_phase(KP P, const float* g, const float* MODl, int shc, int scc, bool from_input, int npart) {
;     ...
;         for (int u = 0; u < RU; ++u) { const int row = row0 + u * NGW; ss[u] = 0.f;
;             if (row < M) { const int b = row / RPB, t = row - b * RPB;
;                 const float4* h = from_input ? (t < SEQ ? (const float4*)(P->x + ((size_t)b * SEQ + t) * DM) : (const float4*)(P->ctx + ((size_t)b * CTXL + (t - SEQ)) * DM)) : (const float4*)(H + (size_t)row * DM);
; #pragma unroll
;                 for (int j = 0; j < 4; ++j) { if (from_input) { const f32x4 t4 = __builtin_nontemporal_load((const f32x4*)h + lane + 64 * j); v[u][j] = make_float4(t4[0], t4[1], t4[2], t4[3]); }
;                     else v[u][j] = h[lane + 64 * j]; } } }
.Lnm_fi0_ptrd:
	global_load_dwordx4 v[0:3], v112, s[64:65] offset:0
	global_load_dwordx4 v[4:7], v112, s[64:65] offset:1024
	global_load_dwordx4 v[8:11], v112, s[64:65] offset:2048
	global_load_dwordx4 v[12:15], v112, s[64:65] offset:3072
	s_add_u32 s23, s23, 4
	s_mov_b32 s12, s23
	s_add_i32 s31, s31, s2
	s_cmp_lt_u32 s31, 0x4200
	s_cbranch_scc0 .Lnm_fi_prod
	s_cmp_ge_u32 s31, 0x2100
	s_cselect_b32 s6, 1, 0
	s_mul_i32 s7, s6, 0x2100
	s_sub_u32 s7, s31, s7
	s_cmp_ge_u32 s7, 0x2000
	s_cbranch_scc1 .Lnm_fi1_ctxp
	s_lshl_b32 s6, s6, 13
	s_add_u32 s6, s6, s7
	s_lshl_b32 s6, s6, 12
	s_add_u32 s64, s20, s6
	s_addc_u32 s65, s21, 0
	s_branch .Lnm_fi1_ptrd

; __device__ __forceinline__ void norm_phase(KP P, const float* g, const float* MODl, int shc, int scc, bool from_input, int npart) {
;     ...
;         for (int u = 0; u < RU; ++u) { const int row = row0 + u * NGW; ss[u] = 0.f;
;             if (row < M) { const int b = row / RPB, t = row - b * RPB;
;                 const float4* h = from_input ? (t < SEQ ? (const float4*)(P->x + ((size_t)b * SEQ + t) * DM) : (const float4*)(P->ctx + ((size_t)b * CTXL + (t - SEQ)) * DM)) : (const float4*)(H + (size_t)row * DM);
; #pragma unroll
;                 for (int j = 0; j < 4; ++j) { if (from_input) { const f32x4 t4 = __builtin_nontemporal_load((const f32x4*)h + lane + 64 * j); v[u][j] = make_float4(t4[0], t4[1], t4[2], t4[3]); }
;                     else v[u][j] = h[lane + 64 * j]; } } }
.Lnm_fi1_ptrd:
	global_load_dwordx4 v[16:19], v112, s[64:65] offset:0
	global_load_dwordx4 v[20:23], v112, s[64:65] offset:1024
	global_load_dwordx4 v[24:27], v112, s[64:65] offset:2048
	global_load_dwordx4 v[28:31], v112, s[64:65] offset:3072
	s_add_u32 s23, s23, 4
	s_mov_b32 s13, s23
	s_add_i32 s31, s31, s2
	s_cmp_lt_u32 s31, 0x4200
	s_cbranch_scc0 .Lnm_fi_prod
	s_cmp_ge_u32 s31, 0x2100
	s_cselect_b32 s6, 1, 0
	s_mul_i32 s7, s6, 0x2100
	s_sub_u32 s7, s31, s7
	s_cmp_ge_u32 s7, 0x2000
	s_cbranch_scc1 .Lnm_fi2_ctxp
	s_lshl_b32 s6, s6, 13
	s_add_u32 s6, s6, s7
	s_lshl_b32 s6, s6, 12
	s_add_u32 s64, s20, s6
	s_addc_u32 s65, s21, 0
	s_branch .Lnm_fi2_ptrd

; __device__ __forceinline__ void norm_phase(KP P, const float* g, const float* MODl, int shc, int scc, bool from_input, int npart) {
;     ...
;         for (int u = 0; u < RU; ++u) { const int row = row0 + u * NGW; ss[u] = 0.f;
;             if (row < M) { const int b = row / RPB, t = row - b * RPB;
;                 const float4* h = from_input ? (t < SEQ ? (const float4*)(P->x + ((size_t)b * SEQ + t) * DM) : (const float4*)(P->ctx + ((size_t)b * CTXL + (t - SEQ)) * DM)) : (const float4*)(H + (size_t)row * DM);
; #pragma unroll
;                 for (int j = 0; j < 4; ++j) { if (from_input) { const f32x4 t4 = __builtin_nontemporal_load((const f32x4*)h + lane + 64 * j); v[u][j] = make_float4(t4[0], t4[1], t4[2], t4[3]); }
;                     else v[u][j] = h[lane + 64 * j]; } } }
.Lnm_fi2_ptrd:
	global_load_dwordx4 v[32:35], v112, s[64:65] offset:0
	global_load_dwordx4 v[36:39], v112, s[64:65] offset:1024
	global_load_dwordx4 v[40:43], v112, s[64:65] offset:2048
	global_load_dwordx4 v[44:47], v112, s[64:65] offset:3072
	s_add_u32 s23, s23, 4
	s_mov_b32 s14, s23
	s_add_i32 s31, s31, s2
	s_cmp_lt_u32 s31, 0x4200
	s_cbranch_scc0 .Lnm_fi_prod
	s_cmp_ge_u32 s31, 0x2100
	s_cselect_b32 s6, 1, 0
	s_mul_i32 s7, s6, 0x2100
	s_sub_u32 s7, s31, s7
	s_cmp_ge_u32 s7, 0x2000
	s_cbranch_scc1 .Lnm_fi3_ctxp
	s_lshl_b32 s6, s6, 13
	s_add_u32 s6, s6, s7
	s_lshl_b32 s6, s6, 12
	s_add_u32 s64, s20, s6
	s_addc_u32 s65, s21, 0
	s_branch .Lnm_fi3_ptrd

; __device__ __forceinline__ void norm_phase(KP P, const float* g, const float* MODl, int shc, int scc, bool from_input, int npart) {
;     ...
;         for (int u = 0; u < RU; ++u) { const int row = row0 + u * NGW; ss[u] = 0.f;
;             if (row < M) { const int b = row / RPB, t = row - b * RPB;
;                 const float4* h = from_input ? (t < SEQ ? (const float4*)(P->x + ((size_t)b * SEQ + t) * DM) : (const float4*)(P->ctx + ((size_t)b * CTXL + (t - SEQ)) * DM)) : (const float4*)(H + (size_t)row * DM);
; #pragma unroll
;                 for (int j = 0; j < 4; ++j) { if (from_input) { const f32x4 t4 = __builtin_nontemporal_load((const f32x4*)h + lane + 64 * j); v[u][j] = make_float4(t4[0], t4[1], t4[2], t4[3]); }
;                     else v[u][j] = h[lane + 64 * j]; } } }
.Lnm_fi3_ptrd:
	global_load_dwordx4 v[48:51], v112, s[64:65] offset:0
	global_load_dwordx4 v[52:55], v112, s[64:65] offset:1024
	global_load_dwordx4 v[56:59], v112, s[64:65] offset:2048
	global_load_dwordx4 v[60:63], v112, s[64:65] offset:3072
	s_add_u32 s23, s23, 4
	s_mov_b32 s15, s23

; __device__ __forceinline__ void norm_phase(KP P, const float* g, const float* MODl, int shc, int scc, bool from_input, int npart) {
;     ...
;         for (int u = 0; u < RU; ++u) { const int row = row0 + u * NGW; ss[u] = 0.f;
;             if (row < M) { const int b = row / RPB, t = row - b * RPB;
;                 const float4* h = from_input ? (t < SEQ ? (const float4*)(P->x + ((size_t)b * SEQ + t) * DM) : (const float4*)(P->ctx + ((size_t)b * CTXL + (t - SEQ)) * DM)) : (const float4*)(H + (size_t)row * DM);
; #pragma unroll
;                 for (int j = 0; j < 4; ++j) { if (from_input) { const f32x4 t4 = __builtin_nontemporal_load((const f32x4*)h + lane + 64 * j); v[u][j] = make_float4(t4[0], t4[1], t4[2], t4[3]); }
;                     else v[u][j] = h[lane + 64 * j]; } } }
.Lnm_fi4_ptrd:
	global_load_dwordx4 v[0:3], v112, s[64:65] offset:0
	global_load_dwordx4 v[4:7], v112, s[64:65] offset:1024
	global_load_dwordx4 v[8:11], v112, s[64:65] offset:2048
	global_load_dwordx4 v[12:15], v112, s[64:65] offset:3072
	s_add_u32 s23, s23, 4
	s_mov_b32 s12, s23

; __device__ __forceinline__ void norm_phase(KP P, const float* g, const float* MODl, int shc, int scc, bool from_input, int npart) {
;     ...
;         for (int u = 0; u < RU; ++u) { const int row = row0 + u * NGW; ss[u] = 0.f;
;             if (row < M) { const int b = row / RPB, t = row - b * RPB;
;                 const float4* h = from_input ? (t < SEQ ? (const float4*)(P->x + ((size_t)b * SEQ + t) * DM) : (const float4*)(P->ctx + ((size_t)b * CTXL + (t - SEQ)) * DM)) : (const float4*)(H + (size_t)row * DM);
; #pragma unroll
;                 for (int j = 0; j < 4; ++j) { if (from_input) { const f32x4 t4 = __builtin_nontemporal_load((const f32x4*)h + lane + 64 * j); v[u][j] = make_float4(t4[0], t4[1], t4[2], t4[3]); }
;                     else v[u][j] = h[lane + 64 * j]; } } }
.Lnm_fi5_ptrd:
	global_load_dwordx4 v[16:19], v112, s[64:65] offset:0
	global_load_dwordx4 v[20:23], v112, s[64:65] offset:1024
	global_load_dwordx4 v[24:27], v112, s[64:65] offset:2048
	global_load_dwordx4 v[28:31], v112, s[64:65] offset:3072
	s_add_u32 s23, s23, 4
	s_mov_b32 s13, s23

; __device__ __forceinline__ void norm_phase(KP P, const float* g, const float* MODl, int shc, int scc, bool from_input, int npart) {
;     ...
;         for (int u = 0; u < RU; ++u) { const int row = row0 + u * NGW; ss[u] = 0.f;
;             if (row < M) { const int b = row / RPB, t = row - b * RPB;
;                 const float4* h = from_input ? (t < SEQ ? (const float4*)(P->x + ((size_t)b * SEQ + t) * DM) : (const float4*)(P->ctx + ((size_t)b * CTXL + (t - SEQ)) * DM)) : (const float4*)(H + (size_t)row * DM);
; #pragma unroll
;                 for (int j = 0; j < 4; ++j) { if (from_input) { const f32x4 t4 = __builtin_nontemporal_load((const f32x4*)h + lane + 64 * j); v[u][j] = make_float4(t4[0], t4[1], t4[2], t4[3]); }
;                     else v[u][j] = h[lane + 64 * j]; } } }
.Lnm_fi6_ptrd:
	global_load_dwordx4 v[32:35], v112, s[64:65] offset:0
	global_load_dwordx4 v[36:39], v112, s[64:65] offset:1024
	global_load_dwordx4 v[40:43], v112, s[64:65] offset:2048
	global_load_dwordx4 v[44:47], v112, s[64:65] offset:3072
	s_add_u32 s23, s23, 4
	s_mov_b32 s14, s23
